# MLA prep loop: six row-chunk loads per iteration issued together into separate registers (one wait instead of six serialized round trips)
# speedup vs baseline: 1.0030x; 1.0016x over previous
.LBB0_288:
	v_add_u32_e32 v14, s21, v19
	v_ashrrev_i32_e32 v15, 31, v14
	s_waitcnt lgkmcnt(0)
	v_lshlrev_b64 v[0:1], 13, v[14:15]
	v_lshl_add_u64 v[16:17], s[8:9], 0, v[0:1]
	v_lshl_add_u64 v[30:31], v[16:17], 0, v[232:233]
	global_load_dwordx4 v[0:3], v[30:31], off
	v_mov_b32_e32 v198, v10
	v_mov_b32_e32 v199, v233
	v_lshl_add_u64 v[196:197], v[16:17], 0, v[198:199]
	global_load_dwordx4 v[176:179], v[30:31], off offset:16
	global_load_dwordx4 v[180:183], v[30:31], off offset:32
	global_load_dwordx4 v[184:187], v[30:31], off offset:48
	global_load_dwordx4 v[188:191], v[196:197], off offset:512
	global_load_dwordx4 v[192:195], v[196:197], off offset:528
	s_waitcnt vmcnt(0) lgkmcnt(0)
	v_lshlrev_b32_e32 v25, 16, v0
	v_and_b32_e32 v0, 0xffff0000, v0
	v_mul_f32_e32 v13, v0, v0
	v_lshlrev_b32_e32 v27, 16, v1
	v_and_b32_e32 v26, 0xffff0000, v1
	v_lshlrev_b32_e32 v24, 16, v2
	v_and_b32_e32 v23, 0xffff0000, v2
	v_lshlrev_b32_e32 v22, 16, v3
	v_and_b32_e32 v21, 0xffff0000, v3
	v_fmac_f32_e32 v13, v25, v25
	v_fmac_f32_e32 v13, v27, v27
	v_fmac_f32_e32 v13, v26, v26
	v_fmac_f32_e32 v13, v24, v24
	v_fmac_f32_e32 v13, v23, v23
	v_fmac_f32_e32 v13, v22, v22
	v_fmac_f32_e32 v13, v21, v21
	v_lshlrev_b32_e32 v11, 16, v176
	v_and_b32_e32 v0, 0xffff0000, v176
	v_mul_f32_e32 v28, v0, v0
	v_fmac_f32_e32 v28, v11, v11
	v_lshlrev_b32_e32 v0, 16, v177
	v_fmac_f32_e32 v28, v0, v0
	v_and_b32_e32 v0, 0xffff0000, v177
	v_fmac_f32_e32 v28, v0, v0
	v_lshlrev_b32_e32 v0, 16, v178
	v_fmac_f32_e32 v28, v0, v0
	v_and_b32_e32 v0, 0xffff0000, v178
	v_fmac_f32_e32 v28, v0, v0
	v_lshlrev_b32_e32 v0, 16, v179
	v_fmac_f32_e32 v28, v0, v0
	v_and_b32_e32 v0, 0xffff0000, v179
	v_fmac_f32_e32 v28, v0, v0
	v_lshlrev_b32_e32 v11, 16, v180
	v_and_b32_e32 v0, 0xffff0000, v180
	v_mul_f32_e32 v29, v0, v0
	v_fmac_f32_e32 v29, v11, v11
	v_lshlrev_b32_e32 v0, 16, v181
	v_fmac_f32_e32 v29, v0, v0
	v_and_b32_e32 v0, 0xffff0000, v181
	v_fmac_f32_e32 v29, v0, v0
	v_lshlrev_b32_e32 v0, 16, v182
	v_fmac_f32_e32 v29, v0, v0
	v_and_b32_e32 v0, 0xffff0000, v182
	v_fmac_f32_e32 v29, v0, v0
	v_lshlrev_b32_e32 v0, 16, v183
	v_fmac_f32_e32 v29, v0, v0
	v_and_b32_e32 v0, 0xffff0000, v183
	v_fmac_f32_e32 v29, v0, v0
	v_lshlrev_b32_e32 v11, 16, v184
	v_and_b32_e32 v0, 0xffff0000, v184
	v_mul_f32_e32 v30, v0, v0
	v_fmac_f32_e32 v30, v11, v11
	v_lshlrev_b32_e32 v0, 16, v185
	v_fmac_f32_e32 v30, v0, v0
	v_and_b32_e32 v0, 0xffff0000, v185
	v_fmac_f32_e32 v30, v0, v0
	v_lshlrev_b32_e32 v0, 16, v186
	v_fmac_f32_e32 v30, v0, v0
	v_and_b32_e32 v0, 0xffff0000, v186
	v_fmac_f32_e32 v30, v0, v0
	v_lshlrev_b32_e32 v0, 16, v187
	v_mov_b32_e32 v11, v233
	v_fmac_f32_e32 v30, v0, v0
	v_and_b32_e32 v0, 0xffff0000, v187
	v_lshl_add_u64 v[32:33], v[16:17], 0, v[10:11]
	v_fmac_f32_e32 v30, v0, v0
	v_lshlrev_b32_e32 v11, 16, v188
	v_and_b32_e32 v0, 0xffff0000, v188
	v_mul_f32_e32 v31, v0, v0
	v_fmac_f32_e32 v31, v11, v11
	v_lshlrev_b32_e32 v0, 16, v189
	v_fmac_f32_e32 v31, v0, v0
	v_and_b32_e32 v0, 0xffff0000, v189
	v_fmac_f32_e32 v31, v0, v0
	v_lshlrev_b32_e32 v0, 16, v190
	v_fmac_f32_e32 v31, v0, v0
	v_and_b32_e32 v0, 0xffff0000, v190
	v_fmac_f32_e32 v31, v0, v0
	v_lshlrev_b32_e32 v0, 16, v191
	v_fmac_f32_e32 v31, v0, v0
	v_and_b32_e32 v0, 0xffff0000, v191
	v_fmac_f32_e32 v31, v0, v0
	v_lshlrev_b32_e32 v11, 16, v192
	v_and_b32_e32 v0, 0xffff0000, v192
	v_mul_f32_e32 v0, v0, v0
	v_fmac_f32_e32 v0, v11, v11
	v_lshlrev_b32_e32 v11, 16, v193
	v_fmac_f32_e32 v0, v11, v11
	v_and_b32_e32 v1, 0xffff0000, v193
	v_fmac_f32_e32 v0, v1, v1
	v_lshlrev_b32_e32 v1, 16, v194
	v_fmac_f32_e32 v0, v1, v1
	v_and_b32_e32 v1, 0xffff0000, v194
	v_fmac_f32_e32 v0, v1, v1
	v_lshlrev_b32_e32 v1, 16, v195
	v_fmac_f32_e32 v0, v1, v1
	v_and_b32_e32 v1, 0xffff0000, v195
	v_fmac_f32_e32 v0, v1, v1
	v_add_f32_e32 v1, v13, v28
	v_add_f32_e32 v1, v1, v29
	v_add_f32_e32 v1, v1, v30
	ds_swizzle_b32 v2, v1 offset:swizzle(SWAP,1)
	v_add_f32_e32 v0, v31, v0
	s_waitcnt lgkmcnt(0)
	v_add_f32_e32 v1, v1, v2
	ds_swizzle_b32 v2, v0 offset:swizzle(SWAP,1)
	s_waitcnt lgkmcnt(0)
	v_add_f32_e32 v2, v0, v2
	ds_swizzle_b32 v0, v1 offset:swizzle(SWAP,2)
	s_waitcnt lgkmcnt(0)
	v_add_f32_e32 v0, v1, v0
	ds_swizzle_b32 v1, v2 offset:swizzle(SWAP,2)
	s_waitcnt lgkmcnt(0)
	v_add_f32_e32 v2, v2, v1
	ds_swizzle_b32 v1, v0 offset:swizzle(SWAP,4)
	ds_swizzle_b32 v3, v2 offset:swizzle(SWAP,4)
	s_and_saveexec_b64 s[14:15], s[2:3]
	s_cbranch_execz .LBB0_290
	s_waitcnt lgkmcnt(1)
	v_add_f32_e32 v0, v0, v1
	v_fmamk_f32 v0, v0, 0x3b800000, v249
	v_cmp_gt_f32_e32 vcc, s84, v0
	v_mul_f32_e32 v1, 0x4f800000, v0
	s_waitcnt lgkmcnt(0)
	v_add_f32_e32 v2, v2, v3
	v_cndmask_b32_e32 v0, v0, v1, vcc
	v_sqrt_f32_e32 v1, v0
	v_fmamk_f32 v2, v2, 0x3c000000, v249
	v_add_u32_e32 v3, -1, v1
	v_fma_f32 v11, -v3, v1, v0
	v_cmp_ge_f32_e64 s[6:7], 0, v11
	v_add_u32_e32 v11, 1, v1
	s_nop 0
	v_cndmask_b32_e64 v3, v1, v3, s[6:7]
	v_fma_f32 v1, -v11, v1, v0
	v_cmp_lt_f32_e64 s[6:7], 0, v1
	s_nop 1
	v_cndmask_b32_e64 v1, v3, v11, s[6:7]
	v_mul_f32_e32 v3, 0x37800000, v1
	v_cndmask_b32_e32 v1, v1, v3, vcc
	v_cmp_class_f32_e32 vcc, v0, v248
	v_mul_f32_e32 v3, 0x4f800000, v2
	s_nop 0
	v_cndmask_b32_e32 v11, v1, v0, vcc
	v_cmp_gt_f32_e32 vcc, s84, v2
	v_lshl_add_u64 v[0:1], v[14:15], 3, s[10:11]
	s_nop 0
	v_cndmask_b32_e32 v2, v2, v3, vcc
	v_sqrt_f32_e32 v3, v2
	s_nop 0
	v_add_u32_e32 v13, -1, v3
	v_fma_f32 v21, -v13, v3, v2
	v_cmp_ge_f32_e64 s[6:7], 0, v21
	v_add_u32_e32 v21, 1, v3
	s_nop 0
	v_cndmask_b32_e64 v13, v3, v13, s[6:7]
	v_fma_f32 v3, -v21, v3, v2
	v_cmp_lt_f32_e64 s[6:7], 0, v3
	s_nop 1
	v_cndmask_b32_e64 v3, v13, v21, s[6:7]
	v_mul_f32_e32 v13, 0x37800000, v3
	v_cndmask_b32_e32 v3, v3, v13, vcc
	v_cmp_class_f32_e32 vcc, v2, v248
	s_nop 1
	v_cndmask_b32_e32 v2, v3, v2, vcc
	v_div_scale_f32 v3, s[6:7], v2, v2, 1.0
	v_rcp_f32_e32 v13, v3
	s_nop 0
	v_fma_f32 v21, -v3, v13, 1.0
	v_fmac_f32_e32 v13, v21, v13
	v_div_scale_f32 v21, vcc, 1.0, v2, 1.0
	v_mul_f32_e32 v22, v21, v13
	v_fma_f32 v23, -v3, v22, v21
	v_fmac_f32_e32 v22, v23, v13
	v_fma_f32 v3, -v3, v22, v21
	v_div_fmas_f32 v3, v3, v13, v22
	v_div_fixup_f32 v3, v3, v2, 1.0
	v_div_scale_f32 v2, s[6:7], v11, v11, 1.0
	v_rcp_f32_e32 v13, v2
	s_nop 0
	v_fma_f32 v21, -v2, v13, 1.0
	v_fmac_f32_e32 v13, v21, v13
	v_div_scale_f32 v21, vcc, 1.0, v11, 1.0
	v_mul_f32_e32 v22, v21, v13
	v_fma_f32 v23, -v2, v22, v21
	v_fmac_f32_e32 v22, v23, v13
	v_fma_f32 v2, -v2, v22, v21
	v_div_fmas_f32 v2, v2, v13, v22
	v_div_fixup_f32 v2, v2, v11, 1.0
	global_store_dwordx2 v[0:1], v[2:3], off
